# redundant workgroup barrier removal: s_barrier between the w_out transposes and the pooling stage (per-wave LDS scratch only) and the second of two back-to-back barriers at P3 entry
# speedup vs baseline: 1.0018x; 1.0018x over previous
.LBB0_380:
	v_add_u32_e32 v133, s97, v170
	v_add_u32_e32 v134, s59, v133
	s_add_u32 s6, s92, 0xca00000
	s_mov_b32 s0, 0x20000
	s_addc_u32 s7, s93, 0
	v_cmp_gt_i32_e32 vcc, s0, v134
	s_and_saveexec_b64 s[8:9], vcc
	v_readlane_b32 s86, v238, 13
	v_readlane_b32 s87, v238, 14
	s_cbranch_execz .LBB0_455
	s_add_u32 s10, s92, 0x4602000
	s_addc_u32 s11, s93, 0
	v_lshlrev_b32_e32 v135, 3, v134
	s_lshl_b32 s43, s94, 12
	s_mov_b64 s[40:41], 0
	v_mov_b32_e32 v93, 0
	s_mov_b32 s42, 0x3e000000
	s_mov_b32 s54, 0x3e800000
	v_mov_b32_e32 v136, v134
	s_branch .LBB0_384

.LBB0_552:
	v_writelane_b32 v238, s22, 17
	s_nop 1
	v_writelane_b32 v238, s23, 18
	s_or_b64 exec, exec, s[10:11]
	v_readlane_b32 s0, v239, 2
	s_and_b64 vcc, exec, s[4:5]
	s_waitcnt lgkmcnt(0)
	v_mbcnt_lo_u32_b32 v135, -1, 0
	v_mbcnt_hi_u32_b32 v135, -1, v135
	s_cbranch_vccz .LBB0_572
	v_add_u32_e32 v137, s97, v135
	v_ashrrev_i32_e32 v134, 6, v137
	v_lshlrev_b32_e32 v1, 3, v137
	v_lshlrev_b32_e32 v2, 4, v137
	v_lshlrev_b32_e32 v141, 5, v134
	v_and_b32_e32 v138, 15, v135
	v_bfe_u32 v136, v135, 4, 2
	v_mov_b32_e32 v65, 0
	v_and_b32_e32 v64, 0x1f0, v2
	v_and_b32_e32 v68, 0xffffff00, v1
	v_lshlrev_b32_e32 v1, 4, v135
	v_add_u32_e32 v3, 0x200, v137
	v_add_u32_e32 v4, 0x400, v137
	v_add_u32_e32 v5, 0x600, v137
	v_add_u32_e32 v6, 0x800, v137
	v_add_u32_e32 v7, 0xa00, v137
	v_add_u32_e32 v8, 0xc00, v137
	v_add_u32_e32 v9, 0xe00, v137
	v_add_u32_e32 v10, 0x1000, v137
	v_add_u32_e32 v11, 0x1200, v137
	v_add_u32_e32 v12, 0x1400, v137
	v_add_u32_e32 v13, 0x1600, v137
	v_add_u32_e32 v14, 0x1800, v137
	v_add_u32_e32 v15, 0x1a00, v137
	v_add_u32_e32 v16, 0x1c00, v137
	v_add_u32_e32 v17, 0x1e00, v137
	v_or_b32_e32 v142, 16, v141
	v_lshl_add_u64 v[66:67], s[68:69], 0, v[64:65]
	v_and_b32_e32 v1, 0x1f0, v1
	v_ashrrev_i32_e32 v2, 5, v137
	s_movk_i32 s0, 0x210
	v_ashrrev_i32_e32 v3, 5, v3
	v_ashrrev_i32_e32 v4, 5, v4
	v_ashrrev_i32_e32 v5, 5, v5
	v_ashrrev_i32_e32 v6, 5, v6
	v_ashrrev_i32_e32 v7, 5, v7
	v_ashrrev_i32_e32 v8, 5, v8
	v_ashrrev_i32_e32 v9, 5, v9
	v_ashrrev_i32_e32 v10, 5, v10
	v_ashrrev_i32_e32 v11, 5, v11
	v_ashrrev_i32_e32 v12, 5, v12
	v_ashrrev_i32_e32 v13, 5, v13
	v_ashrrev_i32_e32 v14, 5, v14
	v_ashrrev_i32_e32 v15, 5, v15
	v_ashrrev_i32_e32 v16, 5, v16
	v_ashrrev_i32_e32 v17, 5, v17
	v_lshlrev_b32_e32 v64, 4, v136
	v_or_b32_e32 v19, v141, v138
	v_or_b32_e32 v20, v142, v138
	v_lshlrev_b32_e32 v0, 3, v136
	v_add_u32_e32 v70, 0x1000, v68
	v_add_u32_e32 v72, 0x2000, v68
	v_add_u32_e32 v74, 0x3000, v68
	v_add_u32_e32 v76, 0x4000, v68
	v_add_u32_e32 v78, 0x5000, v68
	v_add_u32_e32 v80, 0x6000, v68
	v_add_u32_e32 v82, 0x7000, v68
	v_add_u32_e32 v84, 0x8000, v68
	v_add_u32_e32 v86, 0x9000, v68
	v_add_u32_e32 v88, 0xa000, v68
	v_add_u32_e32 v90, 0xb000, v68
	v_add_u32_e32 v92, 0xc000, v68
	v_add_u32_e32 v94, 0xd000, v68
	v_add_u32_e32 v96, 0xe000, v68
	v_add_u32_e32 v98, 0xf000, v68
	v_add_u32_e32 v1, 0, v1
	v_mul_lo_u32 v2, v2, s0
	v_mul_lo_u32 v3, v3, s0
	v_mul_lo_u32 v4, v4, s0
	v_mul_lo_u32 v5, v5, s0
	v_mul_lo_u32 v6, v6, s0
	v_mul_lo_u32 v7, v7, s0
	v_mul_lo_u32 v8, v8, s0
	v_mul_lo_u32 v9, v9, s0
	v_mul_lo_u32 v10, v10, s0
	v_mul_lo_u32 v11, v11, s0
	v_mul_lo_u32 v12, v12, s0
	v_mul_lo_u32 v13, v13, s0
	v_mul_lo_u32 v14, v14, s0
	v_mul_lo_u32 v15, v15, s0
	v_mul_lo_u32 v16, v16, s0
	v_mul_lo_u32 v17, v17, s0
	v_add_u32_e32 v18, 0, v64
	v_mul_lo_u32 v19, v19, s0
	v_mul_lo_u32 v20, v20, s0
	v_mul_u32_u24_e32 v21, 0x210, v138
	v_lshl_or_b32 v139, v134, 4, v138
	v_ashrrev_i32_e32 v69, 31, v68
	v_ashrrev_i32_e32 v71, 31, v70
	v_ashrrev_i32_e32 v73, 31, v72
	s_movk_i32 s18, 0x3000
	v_ashrrev_i32_e32 v75, 31, v74
	v_ashrrev_i32_e32 v77, 31, v76
	v_ashrrev_i32_e32 v79, 31, v78
	v_ashrrev_i32_e32 v81, 31, v80
	v_ashrrev_i32_e32 v83, 31, v82
	v_ashrrev_i32_e32 v85, 31, v84
	v_ashrrev_i32_e32 v87, 31, v86
	v_ashrrev_i32_e32 v89, 31, v88
	v_ashrrev_i32_e32 v91, 31, v90
	v_ashrrev_i32_e32 v93, 31, v92
	v_ashrrev_i32_e32 v95, 31, v94
	v_ashrrev_i32_e32 v97, 31, v96
	v_ashrrev_i32_e32 v99, 31, v98
	v_lshlrev_b32_e32 v140, 2, v136
	v_lshl_add_u64 v[100:101], s[8:9], 0, v[64:65]
	v_add3_u32 v143, v21, v64, 0
	v_lshlrev_b32_e32 v102, 1, v0
	v_add_u32_e32 v144, v1, v2
	v_add_u32_e32 v145, v1, v3
	v_add_u32_e32 v146, v1, v4
	v_add_u32_e32 v147, v1, v5
	v_add_u32_e32 v148, v1, v6
	v_add_u32_e32 v149, v1, v7
	v_add_u32_e32 v150, v1, v8
	v_add_u32_e32 v151, v1, v9
	v_add_u32_e32 v152, v1, v10
	v_add_u32_e32 v153, v1, v11
	v_add_u32_e32 v154, v1, v12
	v_add_u32_e32 v155, v1, v13
	v_add_u32_e32 v156, v1, v14
	v_add_u32_e32 v157, v1, v15
	v_add_u32_e32 v158, v1, v16
	v_add_u32_e32 v159, v1, v17
	s_mov_b64 s[4:5], 0x2800
	v_add_u32_e32 v160, v18, v19
	v_add_u32_e32 v161, v18, v20
	s_mov_b32 s19, s33
	s_mov_b32 s36, s33
	s_branch .LBB0_555
